# GEMM epilogue 16-byte result stores marked non-temporal (nt)
# speedup vs baseline: 1.0041x; 1.0034x over previous
; template <int EPI>
; DI void gemm_phase(const Params& p, char* lds, const bfu* __restrict__ A, const bfu* __restrict__ BT, int ntn, int l, const float* xin) {
;     ...
; #pragma unroll
;         for (int it = 0; it < 8; ++it) {
;           const int id = it * 64 + lane, row = id >> 3, c = id & 7;
;           const uint4 v = *(const uint4*)(stg + row * 144 + c * 16);
;           *(uint4*)(dst + (size_t)row * pitch + c * 8) = v;
;         }
.LBB0_311:
	ds_read_b128 v[0:3], v207
	v_mul_u32_u24_e32 v6, s4, v181
	v_lshl_add_u64 v[4:5], s[6:7], 0, v[196:197]
	v_lshlrev_b32_e32 v196, 1, v6
	v_lshl_add_u64 v[6:7], v[4:5], 0, v[196:197]
	s_waitcnt lgkmcnt(0)
	global_store_dwordx4 v[6:7], v[0:3], off nt
	ds_read_b128 v[0:3], v207 offset:1152
	v_mul_u32_u24_e32 v6, s4, v195
	v_lshlrev_b32_e32 v196, 1, v6
	v_lshl_add_u64 v[6:7], v[4:5], 0, v[196:197]
	s_and_b64 vcc, exec, s[10:11]
	s_waitcnt lgkmcnt(0)
	global_store_dwordx4 v[6:7], v[0:3], off nt
	ds_read_b128 v[0:3], v207 offset:2304
	v_mul_u32_u24_e32 v6, s4, v200
	v_lshlrev_b32_e32 v196, 1, v6
	v_lshl_add_u64 v[6:7], v[4:5], 0, v[196:197]
	s_waitcnt lgkmcnt(0)
	global_store_dwordx4 v[6:7], v[0:3], off nt
	ds_read_b128 v[0:3], v207 offset:3456
	v_mul_u32_u24_e32 v6, s4, v201
	v_lshlrev_b32_e32 v196, 1, v6
	v_lshl_add_u64 v[6:7], v[4:5], 0, v[196:197]
	s_waitcnt lgkmcnt(0)
	global_store_dwordx4 v[6:7], v[0:3], off nt
	ds_read_b128 v[0:3], v207 offset:4608
	v_mul_u32_u24_e32 v6, s4, v202
	v_lshlrev_b32_e32 v196, 1, v6
	v_lshl_add_u64 v[6:7], v[4:5], 0, v[196:197]
	s_waitcnt lgkmcnt(0)
	global_store_dwordx4 v[6:7], v[0:3], off nt
	ds_read_b128 v[0:3], v207 offset:5760
	v_mul_u32_u24_e32 v6, s4, v203
	v_lshlrev_b32_e32 v196, 1, v6
	v_lshl_add_u64 v[6:7], v[4:5], 0, v[196:197]
	s_waitcnt lgkmcnt(0)
	global_store_dwordx4 v[6:7], v[0:3], off nt
	ds_read_b128 v[0:3], v207 offset:6912
	v_mul_u32_u24_e32 v6, s4, v204
	v_lshlrev_b32_e32 v196, 1, v6
	v_lshl_add_u64 v[6:7], v[4:5], 0, v[196:197]
	s_waitcnt lgkmcnt(0)
	global_store_dwordx4 v[6:7], v[0:3], off nt
	ds_read_b128 v[0:3], v207 offset:8064
	v_mul_u32_u24_e32 v6, s4, v205
	v_lshlrev_b32_e32 v196, 1, v6
	v_readlane_b32 s4, v255, 10
	v_lshl_add_u64 v[4:5], v[4:5], 0, v[196:197]
	s_add_i32 s72, s72, s4
	s_waitcnt lgkmcnt(0)
	global_store_dwordx4 v[4:5], v[0:3], off nt
	s_cbranch_vccnz .LBB0_352

; template <int EPI>
; DI void gemm_phase(const Params& p, char* lds, const bfu* __restrict__ A, const bfu* __restrict__ BT, int ntn, int l, const float* xin) {
;     ...
;         if (cls == 1 || cls == 2) {
;           const float* gg = (cls == 1 ? p.qn_g : p.kn_g) + l * 64;
;           const float post = (cls == 1) ? 0.125f * LOG2E : 1.f;
; #pragma unroll
;           for (int i = 0; i < 2; ++i) {
;             float ss = 0.f;
; #pragma unroll
;             for (int j2 = 0; j2 < 2; ++j2)
; #pragma unroll
;               for (int e = 0; e < 16; ++e) ss += acc[i][2 * jp + j2][e] * acc[i][2 * jp + j2][e];
;             ss += __shfl_xor(ss, 32);
;             const float rs = rsqrtf(ss * (1.f / 64.f) + EPS) * post;
; #pragma unroll
;             for (int j2 = 0; j2 < 2; ++j2)
; #pragma unroll
;               for (int g = 0; g < 4; ++g) {
;                 const float4 gv = *(const float4*)(gg + j2 * 32 + 8 * g + 4 * h);
;                 f32x16& a = acc[i][2 * jp + j2];
;                 a[4 * g] *= rs * gv.x; a[4 * g + 1] *= rs * gv.y; a[4 * g + 2] *= rs * gv.z; a[4 * g + 3] *= rs * gv.w;
;               }
;           }
;     ...
; #pragma unroll
;         for (int it = 0; it < 8; ++it) {
;           const int id = it * 64 + lane, row = id >> 3, c = id & 7;
;           const uint4 v = *(const uint4*)(stg + row * 144 + c * 16);
;           *(uint4*)(dst + (size_t)row * pitch + c * 8) = v;
;         }
.LBB0_342:
	ds_read_b128 v[64:67], v207
	v_lshlrev_b32_e32 v196, 1, v180
	v_mul_u32_u24_e32 v70, s4, v181
	v_lshl_add_u64 v[68:69], s[24:25], 0, v[196:197]
	v_lshlrev_b32_e32 v70, 1, v70
	v_mov_b32_e32 v71, v197
	v_lshl_add_u64 v[70:71], v[68:69], 0, v[70:71]
	s_waitcnt lgkmcnt(0)
	global_store_dwordx4 v[70:71], v[64:67], off nt
	ds_read_b128 v[64:67], v207 offset:1152
	v_mul_u32_u24_e32 v70, s4, v195
	v_lshlrev_b32_e32 v70, 1, v70
	v_mov_b32_e32 v71, v197
	v_lshl_add_u64 v[70:71], v[68:69], 0, v[70:71]
	s_waitcnt lgkmcnt(0)
	global_store_dwordx4 v[70:71], v[64:67], off nt
	ds_read_b128 v[64:67], v207 offset:2304
	v_mul_u32_u24_e32 v70, s4, v200
	v_lshlrev_b32_e32 v70, 1, v70
	v_mov_b32_e32 v71, v197
	v_lshl_add_u64 v[70:71], v[68:69], 0, v[70:71]
	s_waitcnt lgkmcnt(0)
	global_store_dwordx4 v[70:71], v[64:67], off nt
	ds_read_b128 v[64:67], v207 offset:3456
	v_mul_u32_u24_e32 v70, s4, v201
	v_lshlrev_b32_e32 v70, 1, v70
	v_mov_b32_e32 v71, v197
	v_lshl_add_u64 v[70:71], v[68:69], 0, v[70:71]
	s_waitcnt lgkmcnt(0)
	global_store_dwordx4 v[70:71], v[64:67], off nt
	ds_read_b128 v[64:67], v207 offset:4608
	v_mul_u32_u24_e32 v70, s4, v202
	v_lshlrev_b32_e32 v70, 1, v70
	v_mov_b32_e32 v71, v197
	v_lshl_add_u64 v[70:71], v[68:69], 0, v[70:71]
	s_waitcnt lgkmcnt(0)
	global_store_dwordx4 v[70:71], v[64:67], off nt
	ds_read_b128 v[64:67], v207 offset:5760
	v_mul_u32_u24_e32 v70, s4, v203
	v_lshlrev_b32_e32 v70, 1, v70
	v_mov_b32_e32 v71, v197
	v_lshl_add_u64 v[70:71], v[68:69], 0, v[70:71]
	s_waitcnt lgkmcnt(0)
	global_store_dwordx4 v[70:71], v[64:67], off nt
	ds_read_b128 v[64:67], v207 offset:6912
	v_mul_u32_u24_e32 v70, s4, v204
	v_lshlrev_b32_e32 v70, 1, v70
	v_mov_b32_e32 v71, v197
	v_lshl_add_u64 v[70:71], v[68:69], 0, v[70:71]
	s_waitcnt lgkmcnt(0)
	global_store_dwordx4 v[70:71], v[64:67], off nt
	ds_read_b128 v[64:67], v207 offset:8064
	v_mul_u32_u24_e32 v70, s4, v205
	v_lshlrev_b32_e32 v70, 1, v70
	v_mov_b32_e32 v71, v197
	v_lshl_add_u64 v[68:69], v[68:69], 0, v[70:71]
	s_andn2_b64 vcc, exec, s[6:7]
	s_waitcnt lgkmcnt(0)
	global_store_dwordx4 v[68:69], v[64:67], off nt
	s_cbranch_vccnz .LBB0_344
	v_cmp_lt_i32_e32 vcc, v239, v238
	v_mov_b32_e32 v66, v17
	v_mov_b32_e32 v67, v49
	v_cndmask_b32_e32 v64, v234, v239, vcc
	v_lshlrev_b32_e32 v113, 2, v64
	v_mov_b32_e32 v64, v16
	v_mov_b32_e32 v65, v48
	v_pk_mul_f32 v[66:67], v[66:67], v[66:67]
	v_readlane_b32 s4, v254, 0
	v_pk_fma_f32 v[64:65], v[64:65], v[64:65], v[66:67]
	v_mov_b32_e32 v66, v18
	v_mov_b32_e32 v67, v50
	v_pk_fma_f32 v[64:65], v[66:67], v[66:67], v[64:65]
	v_mov_b32_e32 v66, v19
	v_mov_b32_e32 v67, v51
	v_pk_fma_f32 v[64:65], v[66:67], v[66:67], v[64:65]
	v_mov_b32_e32 v66, v20
	v_mov_b32_e32 v67, v52
	v_pk_fma_f32 v[64:65], v[66:67], v[66:67], v[64:65]
	v_mov_b32_e32 v66, v21
	v_mov_b32_e32 v67, v53
	v_pk_fma_f32 v[64:65], v[66:67], v[66:67], v[64:65]
	v_mov_b32_e32 v66, v22
	v_mov_b32_e32 v67, v54
	v_readlane_b32 s5, v254, 1
	s_add_u32 s4, s4, s81
	v_pk_fma_f32 v[64:65], v[66:67], v[66:67], v[64:65]
	v_mov_b32_e32 v66, v23
	v_mov_b32_e32 v67, v55
	s_addc_u32 s5, s5, 0
	v_pk_fma_f32 v[64:65], v[66:67], v[66:67], v[64:65]
	v_mov_b32_e32 v66, v24
	v_mov_b32_e32 v67, v56
	s_load_dwordx2 s[4:5], s[4:5], 0x0
	v_pk_fma_f32 v[64:65], v[66:67], v[66:67], v[64:65]
	v_mov_b32_e32 v66, v25
	v_mov_b32_e32 v67, v57
	v_pk_fma_f32 v[64:65], v[66:67], v[66:67], v[64:65]
	v_mov_b32_e32 v66, v26
	v_mov_b32_e32 v67, v58
	v_pk_fma_f32 v[64:65], v[66:67], v[66:67], v[64:65]
	v_mov_b32_e32 v66, v27
	v_mov_b32_e32 v67, v59
	v_pk_fma_f32 v[64:65], v[66:67], v[66:67], v[64:65]
	v_mov_b32_e32 v66, v28
	v_mov_b32_e32 v67, v60
	s_lshl_b64 s[6:7], s[76:77], 2
	v_pk_fma_f32 v[68:69], v[66:67], v[66:67], v[64:65]
	v_mov_b32_e32 v70, v29
	v_mov_b32_e32 v71, v61
	s_waitcnt lgkmcnt(0)
	s_add_u32 s4, s4, s6
	v_pk_fma_f32 v[68:69], v[70:71], v[70:71], v[68:69]
	v_mov_b32_e32 v70, v30
	v_mov_b32_e32 v71, v62
	s_addc_u32 s5, s5, s7
	v_lshlrev_b32_e32 v80, 2, v178
	v_pk_fma_f32 v[68:69], v[70:71], v[70:71], v[68:69]
	v_mov_b32_e32 v70, v31
	v_mov_b32_e32 v71, v63
	global_load_dwordx4 v[64:67], v80, s[4:5]
	global_load_dwordx4 v[84:87], v80, s[4:5] offset:32
	v_pk_fma_f32 v[68:69], v[70:71], v[70:71], v[68:69]
	v_mov_b32_e32 v70, v0
	v_mov_b32_e32 v71, v32
	v_pk_fma_f32 v[68:69], v[70:71], v[70:71], v[68:69]
	v_mov_b32_e32 v70, v1
	v_mov_b32_e32 v71, v33
	v_pk_fma_f32 v[68:69], v[70:71], v[70:71], v[68:69]
	v_mov_b32_e32 v70, v2
	v_mov_b32_e32 v71, v34
	v_pk_fma_f32 v[68:69], v[70:71], v[70:71], v[68:69]
	v_mov_b32_e32 v70, v3
	v_mov_b32_e32 v71, v35
	global_load_dwordx4 v[88:91], v80, s[4:5] offset:64
	global_load_dwordx4 v[92:95], v80, s[4:5] offset:96
	v_pk_fma_f32 v[68:69], v[70:71], v[70:71], v[68:69]
	v_mov_b32_e32 v70, v4
	v_mov_b32_e32 v71, v36
	v_pk_mul_f32 v[76:77], v[38:39], v[38:39]
	v_pk_mul_f32 v[72:73], v[6:7], v[6:7]
	v_pk_fma_f32 v[68:69], v[70:71], v[70:71], v[68:69]
	v_mov_b32_e32 v70, v5
	v_mov_b32_e32 v71, v37
	v_pk_fma_f32 v[68:69], v[70:71], v[70:71], v[68:69]
	v_mov_b32_e32 v70, v72
	v_mov_b32_e32 v71, v76
	v_pk_add_f32 v[78:79], v[70:71], v[68:69]
	global_load_dwordx4 v[68:71], v80, s[4:5] offset:128
	v_mov_b32_e32 v76, v73
	global_load_dwordx4 v[72:75], v80, s[4:5] offset:160
	v_pk_add_f32 v[114:115], v[76:77], v[78:79]
	global_load_dwordx4 v[76:79], v80, s[4:5] offset:192
	v_pk_mul_f32 v[102:103], v[40:41], v[40:41]
	global_load_dwordx4 v[80:83], v80, s[4:5] offset:224
	v_pk_mul_f32 v[110:111], v[8:9], v[8:9]
	v_mov_b32_e32 v117, v102
	v_mov_b32_e32 v116, v110
	v_pk_mul_f32 v[100:101], v[42:43], v[42:43]
	v_pk_mul_f32 v[108:109], v[10:11], v[10:11]
	v_pk_add_f32 v[114:115], v[116:117], v[114:115]
	v_mov_b32_e32 v102, v111
	v_pk_add_f32 v[102:103], v[102:103], v[114:115]
	v_mov_b32_e32 v110, v108
	v_mov_b32_e32 v111, v100
	v_pk_mul_f32 v[98:99], v[44:45], v[44:45]
	v_pk_mul_f32 v[106:107], v[12:13], v[12:13]
	v_pk_add_f32 v[102:103], v[110:111], v[102:103]
	v_mov_b32_e32 v100, v109
	v_pk_add_f32 v[100:101], v[100:101], v[102:103]
	v_mov_b32_e32 v102, v106
	v_mov_b32_e32 v103, v98
	v_pk_mul_f32 v[96:97], v[46:47], v[46:47]
	v_pk_mul_f32 v[104:105], v[14:15], v[14:15]
	v_pk_add_f32 v[100:101], v[102:103], v[100:101]
	v_mov_b32_e32 v98, v107
	v_pk_add_f32 v[98:99], v[98:99], v[100:101]
	v_mov_b32_e32 v100, v104
	v_mov_b32_e32 v101, v96
	v_pk_add_f32 v[98:99], v[100:101], v[98:99]
	v_mov_b32_e32 v96, v105
	v_pk_add_f32 v[96:97], v[96:97], v[98:99]
	ds_bpermute_b32 v99, v113, v97
	ds_bpermute_b32 v98, v113, v96
	s_mov_b32 s2, 0x3c800000
	s_waitcnt lgkmcnt(0)
; template <int EPI>
; DI void gemm_phase(const Params& p, char* lds, const bfu* __restrict__ A, const bfu* __restrict__ BT, int ntn, int l, const float* xin) {
;     ...
;             ss += __shfl_xor(ss, 32);
;             const float rs = rsqrtf(ss * (1.f / 64.f) + EPS) * post;
; #pragma unroll
;             for (int j2 = 0; j2 < 2; ++j2)
; #pragma unroll
;               for (int g = 0; g < 4; ++g) {
;                 const float4 gv = *(const float4*)(gg + j2 * 32 + 8 * g + 4 * h);
;                 f32x16& a = acc[i][2 * jp + j2];
;                 a[4 * g] *= rs * gv.x; a[4 * g + 1] *= rs * gv.y; a[4 * g + 2] *= rs * gv.z; a[4 * g + 3] *= rs * gv.w;
;               }
	v_pk_add_f32 v[96:97], v[96:97], v[98:99]
	s_nop 0
	v_pk_fma_f32 v[96:97], v[96:97], s[2:3], v[198:199] op_sel_hi:[1,0,0]
	s_nop 0
	v_mul_f32_e32 v98, 0x4b800000, v97
	v_cmp_gt_f32_e32 vcc, s99, v97
	v_cmp_gt_f32_e64 s[4:5], s99, v96
	s_nop 0
	v_cndmask_b32_e32 v97, v97, v98, vcc
	v_rsq_f32_e32 v97, v97
	v_mul_f32_e32 v98, 0x4b800000, v96
	v_cndmask_b32_e64 v96, v96, v98, s[4:5]
	v_rsq_f32_e32 v96, v96
	v_mul_f32_e32 v98, 0x45800000, v97
	v_cndmask_b32_e32 v97, v97, v98, vcc
	v_mul_f32_e32 v98, v138, v97
	s_waitcnt vmcnt(7)
	v_pk_mul_f32 v[100:101], v[64:65], v[98:99] op_sel_hi:[1,0]
	v_mul_f32_e32 v97, 0x45800000, v96
	v_pk_mul_f32 v[48:49], v[48:49], v[100:101]
	v_pk_mul_f32 v[100:101], v[66:67], v[98:99] op_sel_hi:[1,0]
	v_cndmask_b32_e64 v96, v96, v97, s[4:5]
	v_pk_mul_f32 v[50:51], v[50:51], v[100:101]
	s_waitcnt vmcnt(6)
	v_pk_mul_f32 v[100:101], v[84:85], v[98:99] op_sel_hi:[1,0]
	v_mul_f32_e32 v96, v138, v96
	v_pk_mul_f32 v[52:53], v[52:53], v[100:101]
	v_pk_mul_f32 v[100:101], v[86:87], v[98:99] op_sel_hi:[1,0]
	v_pk_mul_f32 v[64:65], v[64:65], v[96:97] op_sel_hi:[1,0]
	v_pk_mul_f32 v[54:55], v[54:55], v[100:101]
	s_waitcnt vmcnt(5)
	v_pk_mul_f32 v[100:101], v[88:89], v[98:99] op_sel_hi:[1,0]
	v_pk_mul_f32 v[66:67], v[66:67], v[96:97] op_sel_hi:[1,0]
	v_pk_mul_f32 v[56:57], v[56:57], v[100:101]
	v_pk_mul_f32 v[100:101], v[98:99], v[90:91] op_sel_hi:[0,1]
	v_pk_mul_f32 v[58:59], v[58:59], v[100:101]
	s_waitcnt vmcnt(4)
	v_pk_mul_f32 v[100:101], v[98:99], v[92:93] op_sel_hi:[0,1]
	v_pk_mul_f32 v[60:61], v[60:61], v[100:101]
	v_pk_mul_f32 v[100:101], v[98:99], v[94:95] op_sel_hi:[0,1]
	v_pk_mul_f32 v[84:85], v[84:85], v[96:97] op_sel_hi:[1,0]
	v_pk_mul_f32 v[86:87], v[86:87], v[96:97] op_sel_hi:[1,0]
	v_pk_mul_f32 v[88:89], v[88:89], v[96:97] op_sel_hi:[1,0]
	v_pk_mul_f32 v[90:91], v[90:91], v[96:97] op_sel_hi:[1,0]
	v_pk_mul_f32 v[92:93], v[92:93], v[96:97] op_sel_hi:[1,0]
	v_pk_mul_f32 v[94:95], v[94:95], v[96:97] op_sel_hi:[1,0]
	v_pk_mul_f32 v[18:19], v[18:19], v[66:67]
	v_pk_mul_f32 v[16:17], v[16:17], v[64:65]
	s_waitcnt vmcnt(3)
	v_pk_mul_f32 v[64:65], v[98:99], v[68:69] op_sel_hi:[0,1]
	v_pk_mul_f32 v[66:67], v[98:99], v[70:71] op_sel_hi:[0,1]
	v_pk_mul_f32 v[30:31], v[30:31], v[94:95]
	v_pk_mul_f32 v[28:29], v[28:29], v[92:93]
	v_pk_mul_f32 v[26:27], v[26:27], v[90:91]
	v_pk_mul_f32 v[24:25], v[24:25], v[88:89]
	v_pk_mul_f32 v[22:23], v[22:23], v[86:87]
	v_pk_mul_f32 v[20:21], v[20:21], v[84:85]
	s_waitcnt vmcnt(2)
	v_pk_mul_f32 v[84:85], v[98:99], v[72:73] op_sel_hi:[0,1]
	v_pk_mul_f32 v[86:87], v[98:99], v[74:75] op_sel_hi:[0,1]
	s_waitcnt vmcnt(1)
	v_pk_mul_f32 v[88:89], v[98:99], v[76:77] op_sel_hi:[0,1]
	v_pk_mul_f32 v[90:91], v[98:99], v[78:79] op_sel_hi:[0,1]
	s_waitcnt vmcnt(0)
	v_pk_mul_f32 v[92:93], v[98:99], v[80:81] op_sel_hi:[0,1]
	v_pk_mul_f32 v[94:95], v[98:99], v[82:83] op_sel_hi:[0,1]
	v_pk_mul_f32 v[34:35], v[34:35], v[66:67]
	v_pk_mul_f32 v[32:33], v[32:33], v[64:65]
	v_pk_mul_f32 v[64:65], v[68:69], v[96:97] op_sel_hi:[1,0]
	v_pk_mul_f32 v[66:67], v[70:71], v[96:97] op_sel_hi:[1,0]
	v_pk_mul_f32 v[68:69], v[72:73], v[96:97] op_sel_hi:[1,0]
	v_pk_mul_f32 v[70:71], v[74:75], v[96:97] op_sel_hi:[1,0]
	v_pk_mul_f32 v[72:73], v[76:77], v[96:97] op_sel_hi:[1,0]
	v_pk_mul_f32 v[74:75], v[78:79], v[96:97] op_sel_hi:[1,0]
	v_pk_mul_f32 v[76:77], v[80:81], v[96:97] op_sel_hi:[1,0]
	v_pk_mul_f32 v[78:79], v[82:83], v[96:97] op_sel_hi:[1,0]
	v_pk_mul_f32 v[62:63], v[62:63], v[100:101]
	v_pk_mul_f32 v[46:47], v[46:47], v[94:95]
	v_pk_mul_f32 v[44:45], v[44:45], v[92:93]
	v_pk_mul_f32 v[42:43], v[42:43], v[90:91]
	v_pk_mul_f32 v[40:41], v[40:41], v[88:89]
	v_pk_mul_f32 v[38:39], v[38:39], v[86:87]
	v_pk_mul_f32 v[36:37], v[36:37], v[84:85]
	v_pk_mul_f32 v[14:15], v[14:15], v[78:79]
	v_pk_mul_f32 v[12:13], v[12:13], v[76:77]
	v_pk_mul_f32 v[10:11], v[10:11], v[74:75]
	v_pk_mul_f32 v[8:9], v[8:9], v[72:73]
	v_pk_mul_f32 v[6:7], v[6:7], v[70:71]
	v_pk_mul_f32 v[4:5], v[4:5], v[68:69]
	v_pk_mul_f32 v[2:3], v[2:3], v[66:67]
	v_pk_mul_f32 v[0:1], v[0:1], v[64:65]

; #define SBAR() __builtin_amdgcn_sched_barrier(0)
; template <int EPI>
; DI void gemm_phase(const Params& p, char* lds, const bfu* __restrict__ A, const bfu* __restrict__ BT, int ntn, int l, const float* xin) {
;     ...
;       for (int s = 0; s < 4; ++s) {
;         if (s < 3) {
;           const unsigned co = (unsigned)((((s + 1) * 2 + h) ^ swz) << 4);
;           af[(s + 1) & 1][0] = *(const bf16x8*)(pa + co); af[(s + 1) & 1][1] = *(const bf16x8*)(pa + 4096 + co);
; #pragma unroll
;           for (int j = 0; j < 4; ++j) bfr[(s + 1) & 1][j] = *(const bf16x8*)(pb + j * 4096 + co);
;         }
;         SBAR();
; #pragma unroll
;         for (int i = 0; i < 2; ++i)
; #pragma unroll
;           for (int j = 0; j < 4; ++j) {
;             acc[i][j] = MFMA32(bfr[s & 1][j], af[s & 1][i], acc[i][j]);
;             if (s < 2 && (j & 1) && dnext) DMA_PIECE(dA, dB, dk, dso, s * 4 + i * 2 + (j >> 1));
;           }
;         SBAR();
;       }
;     }
;     WAIT_BAR0();
;     ...
;       char* stg = lds + 65536 + wave * 8704;
;       const float* gate = (const float*)(p.ws + WS_MOD) + l * 6144 + (m0 >> 14) * 3072 + 2048;
;       float4 xn[8];
;     ...
;       LOADX(0);
; #pragma unroll
;       for (int ps = 0; ps < 4; ++ps) {
;         const int i = ps >> 1, jp = ps & 1;
;         float4 xc[8];
; #pragma unroll
;         for (int it = 0; it < 8; ++it) xc[it] = xn[it];
;         if (ps + 1 < 4) LOADX(ps + 1);
;         if (ps) WSYNC();
; #pragma unroll
;         for (int j2 = 0; j2 < 2; ++j2)
; #pragma unroll
;           for (int g = 0; g < 4; ++g) {
;             const f32x16& a = acc[i][2 * jp + j2];
;             float4 o; o.x = a[4 * g]; o.y = a[4 * g + 1]; o.z = a[4 * g + 2]; o.w = a[4 * g + 3];
;             *(float4*)(stg + r * 272 + (j2 * 32 + 8 * g + 4 * h) * 4) = o;
;           }
;         WSYNC();
; #pragma unroll
;         for (int it = 0; it < 8; ++it) {
;           const int id = it * 64 + lane, row = id >> 4, c = id & 15;
;           const float4 y = *(const float4*)(stg + row * 272 + c * 16);
;           const int m = m0 + wm * 64 + i * 32 + row, n = n0 + wn * 128 + jp * 64 + c * 4;
;           const float4 xv = xc[it];
;           const float4 gv = *(const float4*)(gate + n);
;           float4 o; o.x = xv.x + gv.x * y.x; o.y = xv.y + gv.y * y.y; o.z = xv.z + gv.z * y.z; o.w = xv.w + gv.w * y.w;
;           *(float4*)(p.out + (size_t)m * 1024 + n) = o;
;         }
.LBB0_801:
	v_add_u32_e32 v132, v209, v200
	v_add_u32_e32 v148, v210, v200
	ds_read_b128 v[128:131], v132
	ds_read_b128 v[132:135], v132 offset:4096
	ds_read_b128 v[136:139], v148 offset:32768
	ds_read_b128 v[140:143], v148 offset:36864
	ds_read_b128 v[144:147], v148 offset:40960
	ds_read_b128 v[148:151], v148 offset:45056
	s_waitcnt lgkmcnt(9)
	v_mfma_f32_32x32x16_bf16 v[112:127], v[172:175], v[164:167], v[112:127]
	s_waitcnt lgkmcnt(8)
	v_mfma_f32_32x32x16_bf16 v[96:111], v[168:171], v[164:167], v[96:111]
	s_waitcnt lgkmcnt(7)
	v_mfma_f32_32x32x16_bf16 v[80:95], v[160:163], v[164:167], v[80:95]
	s_waitcnt lgkmcnt(6)
	v_mfma_f32_32x32x16_bf16 v[64:79], v[156:159], v[164:167], v[64:79]
	v_mfma_f32_32x32x16_bf16 v[48:63], v[172:175], v[152:155], v[48:63]
	v_mfma_f32_32x32x16_bf16 v[32:47], v[168:171], v[152:155], v[32:47]
	v_mfma_f32_32x32x16_bf16 v[16:31], v[160:163], v[152:155], v[16:31]
	v_mfma_f32_32x32x16_bf16 v[0:15], v[156:159], v[152:155], v[0:15]
	s_waitcnt lgkmcnt(3)
	v_mfma_f32_32x32x16_bf16 v[112:127], v[136:139], v[128:131], v[112:127]
	s_waitcnt lgkmcnt(2)
	v_mfma_f32_32x32x16_bf16 v[96:111], v[140:143], v[128:131], v[96:111]
	s_waitcnt lgkmcnt(1)
	v_mfma_f32_32x32x16_bf16 v[80:95], v[144:147], v[128:131], v[80:95]
	s_waitcnt lgkmcnt(0)
	v_mfma_f32_32x32x16_bf16 v[64:79], v[148:151], v[128:131], v[64:79]
	v_mfma_f32_32x32x16_bf16 v[48:63], v[136:139], v[132:135], v[48:63]
	v_mfma_f32_32x32x16_bf16 v[32:47], v[140:143], v[132:135], v[32:47]
	v_mfma_f32_32x32x16_bf16 v[16:31], v[144:147], v[132:135], v[16:31]
	v_mfma_f32_32x32x16_bf16 v[0:15], v[148:151], v[132:135], v[0:15]
	s_lshr_b32 s4, s35, 6
	s_mulk_i32 s4, 0xc00
	s_ashr_i32 s5, s4, 31
	s_lshl_b64 s[4:5], s[4:5], 2
	s_add_u32 s4, s49, s4
	s_addc_u32 s5, s50, s5
	s_add_i32 s10, s10, s51
	v_or_b32_e32 v128, s10, v201
	v_ashrrev_i32_e32 v129, 31, v128
	v_lshlrev_b64 v[162:163], 12, v[128:129]
	v_or_b32_e32 v128, s10, v202
	v_ashrrev_i32_e32 v129, 31, v128
	v_lshlrev_b64 v[174:175], 12, v[128:129]
	v_or_b32_e32 v128, s10, v203
	v_ashrrev_i32_e32 v129, 31, v128
	v_lshlrev_b64 v[188:189], 12, v[128:129]
	v_or_b32_e32 v128, s10, v204
	v_or_b32_e32 v134, s10, v207
	v_ashrrev_i32_e32 v129, 31, v128
	v_ashrrev_i32_e32 v135, 31, v134
	v_lshlrev_b64 v[150:151], 12, v[128:129]
	v_or_b32_e32 v128, s10, v205
	v_or_b32_e32 v130, s10, v206
	v_lshlrev_b64 v[140:141], 12, v[134:135]
	v_or_b32_e32 v134, s10, v208
	s_waitcnt vmcnt(0) lgkmcnt(0)
	s_barrier
	v_ashrrev_i32_e32 v129, 31, v128
	v_ashrrev_i32_e32 v131, 31, v130
	v_ashrrev_i32_e32 v135, 31, v134
	ds_write_b128 v211, v[112:115]
	ds_write_b128 v211, v[116:119] offset:32
	ds_write_b128 v211, v[120:123] offset:64
	ds_write_b128 v211, v[124:127] offset:96
	ds_write_b128 v211, v[96:99] offset:128
	ds_write_b128 v211, v[100:103] offset:160
	ds_write_b128 v211, v[104:107] offset:192
	ds_write_b128 v211, v[108:111] offset:224
	v_or_b32_e32 v100, s8, v192
	v_lshl_add_u64 v[132:133], s[8:9], 2, v[178:179]
	v_lshlrev_b64 v[148:149], 12, v[128:129]
	v_lshlrev_b64 v[142:143], 12, v[130:131]
	v_lshlrev_b64 v[134:135], 12, v[134:135]
	s_add_u32 s4, s4, 0x26c2000
	v_ashrrev_i32_e32 v101, 31, v100
	v_lshl_add_u64 v[152:153], v[132:133], 0, v[174:175]
	v_lshl_add_u64 v[144:145], v[132:133], 0, v[188:189]
	v_lshl_add_u64 v[136:137], v[132:133], 0, v[150:151]
	v_lshl_add_u64 v[128:129], v[132:133], 0, v[148:149]
	v_lshl_add_u64 v[130:131], v[132:133], 0, v[142:143]
	v_lshl_add_u64 v[138:139], v[132:133], 0, v[140:141]
	v_lshl_add_u64 v[146:147], v[132:133], 0, v[134:135]
	s_addc_u32 s5, s5, 0
	v_lshlrev_b64 v[102:103], 2, v[100:101]
	v_lshl_add_u64 v[164:165], v[132:133], 0, v[162:163]
	v_lshl_add_u64 v[160:161], s[4:5], 0, v[102:103]
	global_load_dwordx4 v[96:99], v[146:147], off offset:256
	global_load_dwordx4 v[108:111], v[146:147], off
	global_load_dwordx4 v[104:107], v[138:139], off offset:256
	global_load_dwordx4 v[116:119], v[138:139], off
	global_load_dwordx4 v[112:115], v[130:131], off offset:256
	global_load_dwordx4 v[124:127], v[130:131], off
	global_load_dwordx4 v[120:123], v[128:129], off offset:256
	global_load_dwordx4 v[156:159], v[128:129], off
	s_nop 0
	global_load_dwordx4 v[128:131], v[136:137], off offset:256
	global_load_dwordx4 v[166:169], v[136:137], off
	s_nop 0
	global_load_dwordx4 v[136:139], v[144:145], off offset:256
	global_load_dwordx4 v[170:173], v[144:145], off
	s_nop 0
	global_load_dwordx4 v[144:147], v[152:153], off offset:256
	global_load_dwordx4 v[184:187], v[152:153], off
	s_nop 0
	global_load_dwordx4 v[152:155], v[164:165], off offset:256
	global_load_dwordx4 v[214:217], v[164:165], off
	s_waitcnt lgkmcnt(0)
	global_load_dwordx4 v[218:221], v[160:161], off
	ds_read_b128 v[222:225], v212
	ds_read_b128 v[226:229], v212 offset:1088
	v_lshl_add_u64 v[164:165], s[28:29], 0, v[102:103]
	v_lshl_add_u64 v[230:231], v[164:165], 0, v[162:163]
	s_or_b32 s8, s10, 32
	v_or_b32_e32 v100, 64, v100
	v_or_b32_e32 v102, s8, v201
	v_ashrrev_i32_e32 v101, 31, v100
	v_ashrrev_i32_e32 v103, 31, v102
	v_lshl_add_u64 v[162:163], v[100:101], 2, s[4:5]
	v_readlane_b32 s4, v255, 10
	s_add_i32 s66, s66, s4
	s_and_b64 vcc, exec, s[6:7]
	s_waitcnt vmcnt(0) lgkmcnt(1)
	v_pk_fma_f32 v[214:215], v[222:223], v[218:219], v[214:215]
	v_pk_fma_f32 v[216:217], v[224:225], v[220:221], v[216:217]
	global_store_dwordx4 v[230:231], v[214:217], off nt
	global_load_dwordx4 v[214:217], v[160:161], off
	v_lshl_add_u64 v[222:223], v[164:165], 0, v[174:175]
	v_lshl_add_u64 v[224:225], v[164:165], 0, v[188:189]
	v_lshlrev_b64 v[188:189], 12, v[102:103]
	ds_read_b128 v[218:221], v212 offset:3264
	s_waitcnt vmcnt(0) lgkmcnt(1)
; #define WSYNC() asm volatile("s_waitcnt lgkmcnt(0)" ::: "memory")
; #define LOADX(ps_) do { _Pragma("unroll") for (int it = 0; it < 8; ++it) { const int id = it * 64 + lane, row = id >> 4, c = id & 15; \
;           xn[it] = *(const float4*)(xin + (size_t)(m0 + wm * 64 + ((ps_) >> 1) * 32 + row) * 1024 + n0 + wn * 128 + ((ps_) & 1) * 64 + c * 4); } } while (0)
; template <int EPI>
; DI void gemm_phase(const Params& p, char* lds, const bfu* __restrict__ A, const bfu* __restrict__ BT, int ntn, int l, const float* xin) {
;     ...
;       for (int ps = 0; ps < 4; ++ps) {
;         const int i = ps >> 1, jp = ps & 1;
;         float4 xc[8];
; #pragma unroll
;         for (int it = 0; it < 8; ++it) xc[it] = xn[it];
;         if (ps + 1 < 4) LOADX(ps + 1);
;         if (ps) WSYNC();
; #pragma unroll
;         for (int j2 = 0; j2 < 2; ++j2)
; #pragma unroll
;           for (int g = 0; g < 4; ++g) {
;             const f32x16& a = acc[i][2 * jp + j2];
;             float4 o; o.x = a[4 * g]; o.y = a[4 * g + 1]; o.z = a[4 * g + 2]; o.w = a[4 * g + 3];
;             *(float4*)(stg + r * 272 + (j2 * 32 + 8 * g + 4 * h) * 4) = o;
;           }
;         WSYNC();
; #pragma unroll
;         for (int it = 0; it < 8; ++it) {
;           const int id = it * 64 + lane, row = id >> 4, c = id & 15;
;           const float4 y = *(const float4*)(stg + row * 272 + c * 16);
;           const int m = m0 + wm * 64 + i * 32 + row, n = n0 + wn * 128 + jp * 64 + c * 4;
;           const float4 xv = xc[it];
;           const float4 gv = *(const float4*)(gate + n);
;           float4 o; o.x = xv.x + gv.x * y.x; o.y = xv.y + gv.y * y.y; o.z = xv.z + gv.z * y.z; o.w = xv.w + gv.w * y.w;
;           *(float4*)(p.out + (size_t)m * 1024 + n) = o;
;         }
	v_pk_fma_f32 v[184:185], v[226:227], v[214:215], v[184:185]
	v_pk_fma_f32 v[186:187], v[228:229], v[216:217], v[186:187]
	global_store_dwordx4 v[222:223], v[184:187], off nt
	global_load_dwordx4 v[184:187], v[160:161], off
	ds_read_b128 v[214:217], v212 offset:2176
	v_lshl_add_u64 v[226:227], v[164:165], 0, v[134:135]
	v_lshl_add_u64 v[228:229], v[132:133], 0, v[188:189]
	s_waitcnt vmcnt(0) lgkmcnt(0)
	v_pk_fma_f32 v[170:171], v[214:215], v[184:185], v[170:171]
	v_pk_fma_f32 v[172:173], v[216:217], v[186:187], v[172:173]
	global_store_dwordx4 v[224:225], v[170:173], off nt
	global_load_dwordx4 v[170:173], v[160:161], off
	v_lshl_add_u64 v[214:215], v[164:165], 0, v[150:151]
	v_lshl_add_u64 v[216:217], v[164:165], 0, v[148:149]
	ds_read_b128 v[148:151], v212 offset:5440
	s_waitcnt vmcnt(0)
	v_pk_fma_f32 v[166:167], v[218:219], v[170:171], v[166:167]
	v_pk_fma_f32 v[168:169], v[220:221], v[172:173], v[168:169]
	global_store_dwordx4 v[214:215], v[166:169], off nt
	global_load_dwordx4 v[166:169], v[160:161], off
	ds_read_b128 v[170:173], v212 offset:4352
	v_lshl_add_u64 v[218:219], v[164:165], 0, v[142:143]
	v_lshl_add_u64 v[220:221], v[164:165], 0, v[140:141]
	ds_read_b128 v[140:143], v212 offset:7616
	s_waitcnt vmcnt(0) lgkmcnt(1)
	v_pk_fma_f32 v[156:157], v[170:171], v[166:167], v[156:157]
	v_pk_fma_f32 v[158:159], v[172:173], v[168:169], v[158:159]
	global_store_dwordx4 v[216:217], v[156:159], off nt
	global_load_dwordx4 v[156:159], v[160:161], off
	v_or_b32_e32 v166, s8, v208
	v_ashrrev_i32_e32 v167, 31, v166
	v_lshlrev_b64 v[166:167], 12, v[166:167]
	v_lshl_add_u64 v[236:237], v[132:133], 0, v[166:167]
	s_waitcnt vmcnt(0)
	v_pk_fma_f32 v[124:125], v[148:149], v[156:157], v[124:125]
	v_pk_fma_f32 v[126:127], v[150:151], v[158:159], v[126:127]
	global_store_dwordx4 v[218:219], v[124:127], off nt
	global_load_dwordx4 v[124:127], v[160:161], off
	ds_read_b128 v[148:151], v212 offset:6528
	v_or_b32_e32 v156, s8, v206
	v_or_b32_e32 v158, s8, v207
	v_ashrrev_i32_e32 v157, 31, v156
	v_ashrrev_i32_e32 v159, 31, v158
	v_lshlrev_b64 v[170:171], 12, v[156:157]
	v_lshlrev_b64 v[168:169], 12, v[158:159]
	v_lshl_add_u64 v[250:251], v[132:133], 0, v[170:171]
	v_lshl_add_u64 v[252:253], v[132:133], 0, v[168:169]
	s_waitcnt vmcnt(0) lgkmcnt(0)
	v_pk_fma_f32 v[116:117], v[148:149], v[124:125], v[116:117]
	v_pk_fma_f32 v[118:119], v[150:151], v[126:127], v[118:119]
	global_store_dwordx4 v[220:221], v[116:119], off nt
	global_load_dwordx4 v[116:119], v[160:161], off
	v_or_b32_e32 v124, s8, v202
	v_or_b32_e32 v126, s8, v203
	v_or_b32_e32 v148, s8, v204
	v_or_b32_e32 v150, s8, v205
	v_ashrrev_i32_e32 v125, 31, v124
	v_ashrrev_i32_e32 v127, 31, v126
	v_ashrrev_i32_e32 v149, 31, v148
	v_ashrrev_i32_e32 v151, 31, v150
	v_lshlrev_b64 v[186:187], 12, v[124:125]
	v_lshlrev_b64 v[184:185], 12, v[126:127]
	v_lshlrev_b64 v[174:175], 12, v[148:149]
	v_lshlrev_b64 v[172:173], 12, v[150:151]
	v_lshl_add_u64 v[232:233], v[132:133], 0, v[186:187]
	v_lshl_add_u64 v[240:241], v[132:133], 0, v[184:185]
	v_lshl_add_u64 v[242:243], v[132:133], 0, v[174:175]
	v_lshl_add_u64 v[248:249], v[132:133], 0, v[172:173]
	s_waitcnt vmcnt(0)
	v_pk_fma_f32 v[100:101], v[140:141], v[116:117], v[108:109]
	v_pk_fma_f32 v[102:103], v[142:143], v[118:119], v[110:111]
	global_store_dwordx4 v[226:227], v[100:103], off nt
	global_load_dwordx4 v[100:103], v[236:237], off
	s_nop 0
	global_load_dwordx4 v[108:111], v[252:253], off
	global_load_dwordx4 v[116:119], v[250:251], off
	global_load_dwordx4 v[124:127], v[248:249], off
	global_load_dwordx4 v[132:135], v[242:243], off
	global_load_dwordx4 v[140:143], v[240:241], off
	global_load_dwordx4 v[148:151], v[232:233], off
	global_load_dwordx4 v[156:159], v[228:229], off
	s_waitcnt lgkmcnt(0)
	ds_write_b128 v211, v[80:83]
	ds_write_b128 v211, v[84:87] offset:32
	ds_write_b128 v211, v[88:91] offset:64
	ds_write_b128 v211, v[92:95] offset:96
	ds_write_b128 v211, v[64:67] offset:128
	ds_write_b128 v211, v[68:71] offset:160
	ds_write_b128 v211, v[72:75] offset:192
	ds_write_b128 v211, v[76:79] offset:224
	s_waitcnt lgkmcnt(0)
	global_load_dwordx4 v[64:67], v[162:163], off
	ds_read_b128 v[68:71], v212
	ds_read_b128 v[72:75], v212 offset:1088
	s_waitcnt vmcnt(0) lgkmcnt(1)
	v_pk_fma_f32 v[64:65], v[68:69], v[64:65], v[152:153]
	v_pk_fma_f32 v[66:67], v[70:71], v[66:67], v[154:155]
	global_store_dwordx4 v[230:231], v[64:67], off offset:256 nt
	global_load_dwordx4 v[64:67], v[162:163], off
	s_waitcnt vmcnt(0) lgkmcnt(0)
	v_pk_fma_f32 v[64:65], v[72:73], v[64:65], v[144:145]
	v_pk_fma_f32 v[66:67], v[74:75], v[66:67], v[146:147]
	global_store_dwordx4 v[222:223], v[64:67], off offset:256 nt
	global_load_dwordx4 v[64:67], v[162:163], off
	ds_read_b128 v[68:71], v212 offset:2176
	ds_read_b128 v[72:75], v212 offset:3264
	s_waitcnt vmcnt(0) lgkmcnt(1)
	v_pk_fma_f32 v[64:65], v[68:69], v[64:65], v[136:137]
	v_pk_fma_f32 v[66:67], v[70:71], v[66:67], v[138:139]
	global_store_dwordx4 v[224:225], v[64:67], off offset:256 nt
	global_load_dwordx4 v[64:67], v[162:163], off
	s_waitcnt vmcnt(0) lgkmcnt(0)
	v_pk_fma_f32 v[64:65], v[72:73], v[64:65], v[128:129]
	v_pk_fma_f32 v[66:67], v[74:75], v[66:67], v[130:131]
	global_store_dwordx4 v[214:215], v[64:67], off offset:256 nt
	global_load_dwordx4 v[64:67], v[162:163], off
	ds_read_b128 v[68:71], v212 offset:4352
	ds_read_b128 v[72:75], v212 offset:5440
	s_waitcnt vmcnt(0) lgkmcnt(1)
	v_pk_fma_f32 v[64:65], v[68:69], v[64:65], v[120:121]
	v_pk_fma_f32 v[66:67], v[70:71], v[66:67], v[122:123]
	global_store_dwordx4 v[216:217], v[64:67], off offset:256 nt
	global_load_dwordx4 v[64:67], v[162:163], off
	s_waitcnt vmcnt(0) lgkmcnt(0)
; #define WSYNC() asm volatile("s_waitcnt lgkmcnt(0)" ::: "memory")
; #define LOADX(ps_) do { _Pragma("unroll") for (int it = 0; it < 8; ++it) { const int id = it * 64 + lane, row = id >> 4, c = id & 15; \
;           xn[it] = *(const float4*)(xin + (size_t)(m0 + wm * 64 + ((ps_) >> 1) * 32 + row) * 1024 + n0 + wn * 128 + ((ps_) & 1) * 64 + c * 4); } } while (0)
; template <int EPI>
; DI void gemm_phase(const Params& p, char* lds, const bfu* __restrict__ A, const bfu* __restrict__ BT, int ntn, int l, const float* xin) {
;     ...
;       for (int ps = 0; ps < 4; ++ps) {
;         const int i = ps >> 1, jp = ps & 1;
;         float4 xc[8];
; #pragma unroll
;         for (int it = 0; it < 8; ++it) xc[it] = xn[it];
;         if (ps + 1 < 4) LOADX(ps + 1);
;         if (ps) WSYNC();
; #pragma unroll
;         for (int j2 = 0; j2 < 2; ++j2)
; #pragma unroll
;           for (int g = 0; g < 4; ++g) {
;             const f32x16& a = acc[i][2 * jp + j2];
;             float4 o; o.x = a[4 * g]; o.y = a[4 * g + 1]; o.z = a[4 * g + 2]; o.w = a[4 * g + 3];
;             *(float4*)(stg + r * 272 + (j2 * 32 + 8 * g + 4 * h) * 4) = o;
;           }
;         WSYNC();
; #pragma unroll
;         for (int it = 0; it < 8; ++it) {
;           const int id = it * 64 + lane, row = id >> 4, c = id & 15;
;           const float4 y = *(const float4*)(stg + row * 272 + c * 16);
;           const int m = m0 + wm * 64 + i * 32 + row, n = n0 + wn * 128 + jp * 64 + c * 4;
;           const float4 xv = xc[it];
;           const float4 gv = *(const float4*)(gate + n);
;           float4 o; o.x = xv.x + gv.x * y.x; o.y = xv.y + gv.y * y.y; o.z = xv.z + gv.z * y.z; o.w = xv.w + gv.w * y.w;
;           *(float4*)(p.out + (size_t)m * 1024 + n) = o;
;         }
	v_pk_fma_f32 v[64:65], v[72:73], v[64:65], v[112:113]
	v_pk_fma_f32 v[66:67], v[74:75], v[66:67], v[114:115]
	global_store_dwordx4 v[218:219], v[64:67], off offset:256 nt
	global_load_dwordx4 v[64:67], v[162:163], off
	ds_read_b128 v[68:71], v212 offset:6528
	ds_read_b128 v[72:75], v212 offset:7616
	s_waitcnt vmcnt(0) lgkmcnt(1)
	v_pk_fma_f32 v[64:65], v[68:69], v[64:65], v[104:105]
	v_pk_fma_f32 v[66:67], v[70:71], v[66:67], v[106:107]
	global_store_dwordx4 v[220:221], v[64:67], off offset:256 nt
	global_load_dwordx4 v[64:67], v[162:163], off
	s_waitcnt vmcnt(0) lgkmcnt(0)
	v_pk_fma_f32 v[64:65], v[72:73], v[64:65], v[96:97]
	v_pk_fma_f32 v[66:67], v[74:75], v[66:67], v[98:99]
	global_store_dwordx4 v[226:227], v[64:67], off offset:256 nt
	global_load_dwordx4 v[64:67], v[236:237], off offset:256
	s_nop 0
	global_load_dwordx4 v[68:71], v[252:253], off offset:256
	global_load_dwordx4 v[72:75], v[250:251], off offset:256
	global_load_dwordx4 v[76:79], v[248:249], off offset:256
	global_load_dwordx4 v[80:83], v[242:243], off offset:256
	global_load_dwordx4 v[84:87], v[240:241], off offset:256
	global_load_dwordx4 v[88:91], v[232:233], off offset:256
	global_load_dwordx4 v[92:95], v[228:229], off offset:256
	s_waitcnt lgkmcnt(0)
	ds_write_b128 v211, v[48:51]
	ds_write_b128 v211, v[52:55] offset:32
	ds_write_b128 v211, v[56:59] offset:64
	ds_write_b128 v211, v[60:63] offset:96
	ds_write_b128 v211, v[32:35] offset:128
	ds_write_b128 v211, v[36:39] offset:160
	ds_write_b128 v211, v[40:43] offset:192
	ds_write_b128 v211, v[44:47] offset:224
	s_waitcnt lgkmcnt(0)
	global_load_dwordx4 v[32:35], v[160:161], off
	ds_read_b128 v[36:39], v212
	ds_read_b128 v[40:43], v212 offset:1088
	v_lshl_add_u64 v[44:45], v[164:165], 0, v[188:189]
	v_lshl_add_u64 v[46:47], v[164:165], 0, v[186:187]
	v_lshl_add_u64 v[48:49], v[164:165], 0, v[184:185]
	v_lshl_add_u64 v[50:51], v[164:165], 0, v[174:175]
	v_lshl_add_u64 v[52:53], v[164:165], 0, v[172:173]
	v_lshl_add_u64 v[54:55], v[164:165], 0, v[170:171]
	v_lshl_add_u64 v[56:57], v[164:165], 0, v[168:169]
	s_waitcnt vmcnt(0) lgkmcnt(1)
	v_pk_fma_f32 v[32:33], v[36:37], v[32:33], v[156:157]
	v_pk_fma_f32 v[34:35], v[38:39], v[34:35], v[158:159]
	global_store_dwordx4 v[44:45], v[32:35], off nt
	global_load_dwordx4 v[32:35], v[160:161], off
	ds_read_b128 v[36:39], v212 offset:2176
	s_waitcnt vmcnt(0) lgkmcnt(1)
	v_pk_fma_f32 v[32:33], v[40:41], v[32:33], v[148:149]
	v_pk_fma_f32 v[34:35], v[42:43], v[34:35], v[150:151]
	global_store_dwordx4 v[46:47], v[32:35], off nt
	global_load_dwordx4 v[32:35], v[160:161], off
	ds_read_b128 v[40:43], v212 offset:3264
	s_waitcnt vmcnt(0) lgkmcnt(1)
	v_pk_fma_f32 v[32:33], v[36:37], v[32:33], v[140:141]
	v_pk_fma_f32 v[34:35], v[38:39], v[34:35], v[142:143]
	global_store_dwordx4 v[48:49], v[32:35], off nt
	global_load_dwordx4 v[32:35], v[160:161], off
	ds_read_b128 v[36:39], v212 offset:4352
	s_waitcnt vmcnt(0) lgkmcnt(1)
	v_pk_fma_f32 v[32:33], v[40:41], v[32:33], v[132:133]
	v_pk_fma_f32 v[34:35], v[42:43], v[34:35], v[134:135]
	global_store_dwordx4 v[50:51], v[32:35], off nt
	global_load_dwordx4 v[32:35], v[160:161], off
	ds_read_b128 v[40:43], v212 offset:5440
	s_waitcnt vmcnt(0) lgkmcnt(1)
	v_pk_fma_f32 v[32:33], v[36:37], v[32:33], v[124:125]
	v_pk_fma_f32 v[34:35], v[38:39], v[34:35], v[126:127]
	global_store_dwordx4 v[52:53], v[32:35], off nt
	global_load_dwordx4 v[32:35], v[160:161], off
	ds_read_b128 v[36:39], v212 offset:6528
	s_waitcnt vmcnt(0) lgkmcnt(1)
	v_pk_fma_f32 v[32:33], v[40:41], v[32:33], v[116:117]
	v_pk_fma_f32 v[34:35], v[42:43], v[34:35], v[118:119]
	global_store_dwordx4 v[54:55], v[32:35], off nt
	global_load_dwordx4 v[32:35], v[160:161], off
	ds_read_b128 v[40:43], v212 offset:7616
	s_waitcnt vmcnt(0) lgkmcnt(1)
	v_pk_fma_f32 v[32:33], v[36:37], v[32:33], v[108:109]
	v_pk_fma_f32 v[34:35], v[38:39], v[34:35], v[110:111]
	global_store_dwordx4 v[56:57], v[32:35], off nt
	global_load_dwordx4 v[32:35], v[160:161], off
	v_lshl_add_u64 v[36:37], v[164:165], 0, v[166:167]
	s_waitcnt vmcnt(0) lgkmcnt(0)
	v_pk_fma_f32 v[32:33], v[40:41], v[32:33], v[100:101]
	v_pk_fma_f32 v[34:35], v[42:43], v[34:35], v[102:103]
	global_store_dwordx4 v[36:37], v[32:35], off nt
	s_waitcnt lgkmcnt(0)
	ds_write_b128 v211, v[16:19]
	ds_write_b128 v211, v[20:23] offset:32
	ds_write_b128 v211, v[24:27] offset:64
	ds_write_b128 v211, v[28:31] offset:96
	ds_write_b128 v211, v[0:3] offset:128
	ds_write_b128 v211, v[4:7] offset:160
	ds_write_b128 v211, v[8:11] offset:192
	ds_write_b128 v211, v[12:15] offset:224
	s_waitcnt lgkmcnt(0)
	global_load_dwordx4 v[0:3], v[162:163], off
	ds_read_b128 v[4:7], v212
	ds_read_b128 v[8:11], v212 offset:1088
	s_waitcnt vmcnt(0) lgkmcnt(1)
	v_pk_fma_f32 v[0:1], v[4:5], v[0:1], v[92:93]
	v_pk_fma_f32 v[2:3], v[6:7], v[2:3], v[94:95]
	global_store_dwordx4 v[44:45], v[0:3], off offset:256 nt
	global_load_dwordx4 v[0:3], v[162:163], off
	s_waitcnt vmcnt(0) lgkmcnt(0)
	v_pk_fma_f32 v[0:1], v[8:9], v[0:1], v[88:89]
	v_pk_fma_f32 v[2:3], v[10:11], v[2:3], v[90:91]
	global_store_dwordx4 v[46:47], v[0:3], off offset:256 nt
	global_load_dwordx4 v[0:3], v[162:163], off
	ds_read_b128 v[4:7], v212 offset:2176
	ds_read_b128 v[8:11], v212 offset:3264
	s_waitcnt vmcnt(0) lgkmcnt(1)
	v_pk_fma_f32 v[0:1], v[4:5], v[0:1], v[84:85]
	v_pk_fma_f32 v[2:3], v[6:7], v[2:3], v[86:87]
	global_store_dwordx4 v[48:49], v[0:3], off offset:256 nt
	global_load_dwordx4 v[0:3], v[162:163], off
	s_waitcnt vmcnt(0) lgkmcnt(0)
	v_pk_fma_f32 v[0:1], v[8:9], v[0:1], v[80:81]
	v_pk_fma_f32 v[2:3], v[10:11], v[2:3], v[82:83]
	global_store_dwordx4 v[50:51], v[0:3], off offset:256 nt
	global_load_dwordx4 v[0:3], v[162:163], off
	ds_read_b128 v[4:7], v212 offset:4352
	ds_read_b128 v[8:11], v212 offset:5440
	s_waitcnt vmcnt(0) lgkmcnt(1)
	v_pk_fma_f32 v[0:1], v[4:5], v[0:1], v[76:77]
	v_pk_fma_f32 v[2:3], v[6:7], v[2:3], v[78:79]
	global_store_dwordx4 v[52:53], v[0:3], off offset:256 nt
	global_load_dwordx4 v[0:3], v[162:163], off
	s_waitcnt vmcnt(0) lgkmcnt(0)
	v_pk_fma_f32 v[0:1], v[8:9], v[0:1], v[72:73]
	v_pk_fma_f32 v[2:3], v[10:11], v[2:3], v[74:75]
	global_store_dwordx4 v[54:55], v[0:3], off offset:256 nt
	global_load_dwordx4 v[0:3], v[162:163], off
	ds_read_b128 v[4:7], v212 offset:6528
	ds_read_b128 v[8:11], v212 offset:7616
	s_waitcnt vmcnt(0) lgkmcnt(1)
	v_pk_fma_f32 v[0:1], v[4:5], v[0:1], v[68:69]
	v_pk_fma_f32 v[2:3], v[6:7], v[2:3], v[70:71]
	global_store_dwordx4 v[56:57], v[0:3], off offset:256 nt
	global_load_dwordx4 v[0:3], v[162:163], off
	s_waitcnt vmcnt(0) lgkmcnt(0)
	v_pk_fma_f32 v[0:1], v[8:9], v[0:1], v[64:65]
	v_pk_fma_f32 v[2:3], v[10:11], v[2:3], v[66:67]
	global_store_dwordx4 v[36:37], v[0:3], off offset:256 nt
	s_cbranch_vccnz .LBB0_822
